# cmp_unit GEMM1 operands staged through LDS with LDS-DMA (3x40KB ring, swizzled tiles) instead of per-lane fragment loads from L2; plus EpiResid dwordx4 epilogue
# speedup vs baseline: 1.0194x; 1.0194x over previous
.LBB0_155:
	s_lshr_b32 s3, s2, 2
	s_and_b32 s9, s2, 3
	s_cmp_gt_u32 s9, 1
	s_cbranch_scc1 .LBB0_197
	s_and_b32 s1, s3, 1
	s_lshl_b32 s42, s1, 6
	s_lshr_b32 s1, s2, 1
	s_and_b32 s8, s2, 1
	s_ashr_i32 s40, s2, 4
	s_and_b32 s1, s1, 2
	v_readlane_b32 s30, v255, 9
	s_bfe_u32 s0, s2, 0x10003
	v_cndmask_b32_e64 v0, 0, 1, s[10:11]
	s_and_b32 s12, s40, -2
	s_or_b32 s1, s1, s8
	v_readlane_b32 s31, v255, 10
	s_mov_b32 s8, 0
	s_lshl_b32 s39, s0, 18
	s_waitcnt vmcnt(0)
	v_lshlrev_b32_e32 v4, 5, v0
	s_lshl_b32 s6, s2, 2
	s_or_b32 s0, s12, s0
	s_and_b32 s6, s6, 64
	v_mbcnt_lo_u32_b32 v0, -1, s8
	s_lshl_b32 s12, s0, 2
	v_mbcnt_hi_u32_b32 v0, -1, v0
	v_readlane_b32 s8, v252, 19
	s_add_i32 s6, s12, s6
	s_lshl_b32 s20, s1, 5
	v_add_u32_e32 v0, s8, v0
	s_and_b32 s8, s0, 15
	s_bfe_u32 s0, s0, 0x30001
	s_cmp_lt_u32 s6, 64
	s_mul_i32 s25, s0, 0x1414000
	s_cselect_b64 s[0:1], -1, 0
	s_cmp_gt_u32 s6, 63
	s_cselect_b64 s[22:23], -1, 0
	v_ashrrev_i32_e32 v18, 6, v0
	s_and_b64 s[28:29], s[0:1], exec
	s_mov_b32 s21, 0x800000
	v_readfirstlane_b32 s12, v18
	s_cselect_b32 s41, s21, 0x880000
	s_mov_b32 s21, 0x3300000
	s_cselect_b32 s43, s21, 0x3380000
	s_ashr_i32 s21, s12, 2
	s_add_u32 s25, s30, s25
	s_addc_u32 s28, s31, 0
	s_add_u32 s25, s25, s41
	v_and_b32_e32 v19, 31, v0
	s_addc_u32 s29, s28, 0
	v_and_b32_e32 v23, 63, v0
	v_bfe_u32 v28, v0, 5, 1
	s_add_u32 s28, s25, s39
	v_or_b32_e32 v0, s20, v19
	s_addc_u32 s29, s29, 0
	v_lshlrev_b32_e32 v0, 11, v0
	v_lshl_add_u64 v[2:3], s[28:29], 0, v[0:1]
	v_lshlrev_b32_e32 v0, 4, v28
	v_lshl_add_u64 v[2:3], v[2:3], 0, v[0:1]
	s_mov_b64 s[28:29], 0x5400000
	s_lshl_b32 s36, s21, 10
	v_lshl_add_u64 v[20:21], v[2:3], 0, s[28:29]
	s_lshl_b32 s28, s21, 6
	s_ashr_i32 s37, s36, 31
	s_and_b32 s44, s12, 3
	v_lshlrev_b32_e32 v2, 12, v19
	s_bfe_u32 s40, s40, 0x30001
	s_or_b32 s25, s28, 48
	s_add_i32 s28, s28, -16
	s_or_b32 s29, s36, 0xc0
	s_or_b32 s33, s36, 0x80
	s_or_b32 s38, s36, 64
	s_lshl_b64 s[36:37], s[36:37], 1
	v_lshl_or_b32 v2, s44, 17, v2
	s_mul_i32 s40, s40, 0x1414000
	v_or3_b32 v2, s43, v0, v2
	v_mov_b32_e32 v3, v1
	s_add_u32 s40, s41, s40
	v_lshl_add_u64 v[24:25], s[30:31], 0, v[2:3]
	s_addc_u32 s41, 0, 0
	v_or_b32_e32 v2, s42, v4
	s_add_u32 s40, s40, s39
	v_or_b32_e32 v2, v2, v19
	s_addc_u32 s41, s41, 0
	v_lshlrev_b32_e32 v2, 11, v2
	v_lshl_add_u64 v[2:3], s[40:41], 0, v[2:3]
	v_or_b32_e32 v2, v2, v0
	v_lshl_add_u64 v[26:27], s[30:31], 0, v[2:3]
	v_mov_b32_e32 v2, 0
	s_mov_b32 s13, 0
	v_lshlrev_b32_e32 v22, 3, v28
	v_mov_b32_e32 v3, v2
	v_mov_b32_e32 v4, v2
	v_mov_b32_e32 v5, v2
	v_mov_b32_e32 v6, v2
	v_mov_b32_e32 v7, v2
	v_mov_b32_e32 v8, v2
	v_mov_b32_e32 v9, v2
	v_mov_b32_e32 v10, v2
	v_mov_b32_e32 v11, v2
	v_mov_b32_e32 v12, v2
	v_mov_b32_e32 v13, v2
	v_mov_b32_e32 v14, v2
	v_mov_b32_e32 v15, v2
	v_mov_b32_e32 v16, v2
	v_mov_b32_e32 v17, v2
	s_lshl_b32 s28, s21, 12
	s_lshl_b32 s13, s44, 10
	s_add_i32 s28, s28, s13
	s_lshl_b32 s29, s21, 2
	s_add_i32 s29, s29, s44
	s_lshl_b32 s29, s29, 12
	s_addk_i32 s29, 0x2000
	s_lshr_b32 s13, s2, 5
	s_mul_i32 s40, s13, 0x1414000
	s_mul_hi_u32 s41, s13, 0x1414000
	s_bfe_u32 s13, s2, 0x10003
	s_lshl_b32 s13, s13, 18
	s_add_u32 s40, s40, s13
	s_addc_u32 s41, s41, 0
	s_bfe_u32 s13, s2, 0x10004
	s_lshl_b32 s25, s13, 19
	s_add_u32 s40, s40, s25
	s_addc_u32 s41, s41, 0
	s_add_u32 s40, s40, 0x5c00000
	s_addc_u32 s41, s41, 0
	s_add_u32 s40, s40, s30
	s_addc_u32 s41, s41, s31
	s_add_u32 s38, s30, s25
	s_addc_u32 s39, s31, 0
	s_add_u32 s38, s38, 0x3300000
	s_addc_u32 s39, s39, 0
	v_lshrrev_b32_e32 v35, 3, v23
	v_and_b32_e32 v36, 7, v23
	v_lshrrev_b32_e32 v37, 1, v35
	v_xor_b32_e32 v36, v36, v37
	v_xor_b32_e32 v37, 4, v36
	s_lshl_b32 s13, s44, 3
	s_add_i32 s13, s13, s20
	s_add_i32 s13, s13, s21
	v_add_u32_e32 v30, s13, v35
	v_lshlrev_b32_e32 v30, 11, v30
	s_bitcmp1_b32 s44, 0
	s_cselect_b64 vcc, -1, 0
	s_nop 1
	v_cndmask_b32_e32 v38, v36, v37, vcc
	v_lshl_add_u32 v30, v38, 4, v30
	s_lshl_b32 s13, s44, 5
	v_add_u32_e32 v38, s13, v35
	v_lshlrev_b32_e32 v38, 12, v38
	s_lshl_b32 s13, s21, 11
	v_add_u32_e32 v38, s13, v38
	v_lshl_add_u32 v31, v36, 4, v38
	v_lshl_add_u32 v32, v37, 4, v38
	v_add_u32_e32 v32, 0x8000, v32
	v_add_u32_e32 v33, 0x10000, v31
	v_add_u32_e32 v34, 0x10000, v32
	v_lshrrev_b32_e32 v35, 1, v19
	v_and_b32_e32 v35, 7, v35
	v_xor_b32_e32 v35, v35, v28
	v_lshlrev_b32_e32 v36, 7, v19
	v_xor_b32_e32 v37, 0, v35
	v_lshl_add_u32 v40, v37, 4, v36
	v_xor_b32_e32 v37, 2, v35
	v_lshl_add_u32 v41, v37, 4, v36
	v_xor_b32_e32 v37, 4, v35
	v_lshl_add_u32 v42, v37, 4, v36
	v_xor_b32_e32 v37, 6, v35
	v_lshl_add_u32 v43, v37, 4, v36
	s_lshl_b32 s13, s21, 12
	v_add_u32_e32 v48, s29, v40
	v_add_u32_e32 v44, s13, v40
	v_add_u32_e32 v49, s29, v41
	v_add_u32_e32 v45, s13, v41
	v_add_u32_e32 v50, s29, v42
	v_add_u32_e32 v46, s13, v42
	v_add_u32_e32 v51, s29, v43
	v_add_u32_e32 v47, s13, v43
	v_add_u32_e32 v52, 0x14000, v44
	v_add_u32_e32 v56, 0x14000, v48
	v_add_u32_e32 v53, 0x14000, v45
	v_add_u32_e32 v57, 0x14000, v49
	v_add_u32_e32 v54, 0x14000, v46
	v_add_u32_e32 v58, 0x14000, v50
	v_add_u32_e32 v55, 0x14000, v47
	v_add_u32_e32 v59, 0x14000, v51
	s_barrier
	s_add_i32 m0, s28, 0x0
	s_nop 0
	global_load_lds_dwordx4 v30, s[40:41]
	s_add_i32 m0, s29, 0x0
	s_nop 0
	global_load_lds_dwordx4 v31, s[38:39]
	s_add_i32 m0, s29, 0x400
	s_nop 0
	global_load_lds_dwordx4 v32, s[38:39]
	s_add_i32 m0, s29, 0x800
	s_nop 0
	global_load_lds_dwordx4 v33, s[38:39]
	s_add_i32 m0, s29, 0xc00
	s_nop 0
	global_load_lds_dwordx4 v34, s[38:39]
	s_add_u32 s40, s40, 0x80
	s_addc_u32 s41, s41, 0
	s_add_u32 s38, s38, 0x80
	s_addc_u32 s39, s39, 0
	s_add_i32 m0, s28, 0xa000
	s_nop 0
	global_load_lds_dwordx4 v30, s[40:41]
	s_add_i32 m0, s29, 0xa000
	s_nop 0
	global_load_lds_dwordx4 v31, s[38:39]
	s_add_i32 m0, s29, 0xa400
	s_nop 0
	global_load_lds_dwordx4 v32, s[38:39]
	s_add_i32 m0, s29, 0xa800
	s_nop 0
	global_load_lds_dwordx4 v33, s[38:39]
	s_add_i32 m0, s29, 0xac00
	s_nop 0
	global_load_lds_dwordx4 v34, s[38:39]
	s_add_u32 s40, s40, 0x80
	s_addc_u32 s41, s41, 0
	s_add_u32 s38, s38, 0x80
	s_addc_u32 s39, s39, 0
	s_waitcnt vmcnt(5)
	s_barrier
	s_add_i32 m0, s28, 0x14000
	s_nop 0
	global_load_lds_dwordx4 v30, s[40:41]
	s_add_i32 m0, s29, 0x14000
	s_nop 0
	global_load_lds_dwordx4 v31, s[38:39]
	s_add_i32 m0, s29, 0x14400
	s_nop 0
	global_load_lds_dwordx4 v32, s[38:39]
	s_add_i32 m0, s29, 0x14800
	s_nop 0
	global_load_lds_dwordx4 v33, s[38:39]
	s_add_i32 m0, s29, 0x14c00
	s_nop 0
	global_load_lds_dwordx4 v34, s[38:39]
	s_add_u32 s40, s40, 0x80
	s_addc_u32 s41, s41, 0
	s_add_u32 s38, s38, 0x80
	s_addc_u32 s39, s39, 0
	ds_read_b128 v[60:63], v44
	ds_read_b128 v[76:79], v48
	ds_read_b128 v[64:67], v45
	ds_read_b128 v[80:83], v49
	ds_read_b128 v[68:71], v46
	ds_read_b128 v[84:87], v50
	ds_read_b128 v[72:75], v47
	ds_read_b128 v[88:91], v51
	s_waitcnt lgkmcnt(6)
	v_mfma_f32_32x32x16_bf16 v[2:17], v[60:63], v[76:79], v[2:17]
	s_waitcnt lgkmcnt(4)
	v_mfma_f32_32x32x16_bf16 v[2:17], v[64:67], v[80:83], v[2:17]
	s_waitcnt lgkmcnt(2)
	v_mfma_f32_32x32x16_bf16 v[2:17], v[68:71], v[84:87], v[2:17]
	s_waitcnt lgkmcnt(0)
	v_mfma_f32_32x32x16_bf16 v[2:17], v[72:75], v[88:91], v[2:17]
	s_waitcnt vmcnt(5)
	s_barrier
	s_add_i32 m0, s28, 0x0
	s_nop 0
	global_load_lds_dwordx4 v30, s[40:41]
	s_add_i32 m0, s29, 0x0
	s_nop 0
	global_load_lds_dwordx4 v31, s[38:39]
	s_add_i32 m0, s29, 0x400
	s_nop 0
	global_load_lds_dwordx4 v32, s[38:39]
	s_add_i32 m0, s29, 0x800
	s_nop 0
	global_load_lds_dwordx4 v33, s[38:39]
	s_add_i32 m0, s29, 0xc00
	s_nop 0
	global_load_lds_dwordx4 v34, s[38:39]
	s_add_u32 s40, s40, 0x80
	s_addc_u32 s41, s41, 0
	s_add_u32 s38, s38, 0x80
	s_addc_u32 s39, s39, 0
	ds_read_b128 v[60:63], v44 offset:40960
	ds_read_b128 v[76:79], v48 offset:40960
	ds_read_b128 v[64:67], v45 offset:40960
	ds_read_b128 v[80:83], v49 offset:40960
	ds_read_b128 v[68:71], v46 offset:40960
	ds_read_b128 v[84:87], v50 offset:40960
	ds_read_b128 v[72:75], v47 offset:40960
	ds_read_b128 v[88:91], v51 offset:40960
	s_waitcnt lgkmcnt(6)
	v_mfma_f32_32x32x16_bf16 v[2:17], v[60:63], v[76:79], v[2:17]
	s_waitcnt lgkmcnt(4)
	v_mfma_f32_32x32x16_bf16 v[2:17], v[64:67], v[80:83], v[2:17]
	s_waitcnt lgkmcnt(2)
	v_mfma_f32_32x32x16_bf16 v[2:17], v[68:71], v[84:87], v[2:17]
	s_waitcnt lgkmcnt(0)
	v_mfma_f32_32x32x16_bf16 v[2:17], v[72:75], v[88:91], v[2:17]
	s_waitcnt vmcnt(5)
	s_barrier
	s_add_i32 m0, s28, 0xa000
	s_nop 0
	global_load_lds_dwordx4 v30, s[40:41]
	s_add_i32 m0, s29, 0xa000
	s_nop 0
	global_load_lds_dwordx4 v31, s[38:39]
	s_add_i32 m0, s29, 0xa400
	s_nop 0
	global_load_lds_dwordx4 v32, s[38:39]
	s_add_i32 m0, s29, 0xa800
	s_nop 0
	global_load_lds_dwordx4 v33, s[38:39]
	s_add_i32 m0, s29, 0xac00
	s_nop 0
	global_load_lds_dwordx4 v34, s[38:39]
	s_add_u32 s40, s40, 0x80
	s_addc_u32 s41, s41, 0
	s_add_u32 s38, s38, 0x80
	s_addc_u32 s39, s39, 0
	ds_read_b128 v[60:63], v52
	ds_read_b128 v[76:79], v56
	ds_read_b128 v[64:67], v53
	ds_read_b128 v[80:83], v57
	ds_read_b128 v[68:71], v54
	ds_read_b128 v[84:87], v58
	ds_read_b128 v[72:75], v55
	ds_read_b128 v[88:91], v59
	s_waitcnt lgkmcnt(6)
	v_mfma_f32_32x32x16_bf16 v[2:17], v[60:63], v[76:79], v[2:17]
	s_waitcnt lgkmcnt(4)
	v_mfma_f32_32x32x16_bf16 v[2:17], v[64:67], v[80:83], v[2:17]
	s_waitcnt lgkmcnt(2)
	v_mfma_f32_32x32x16_bf16 v[2:17], v[68:71], v[84:87], v[2:17]
	s_waitcnt lgkmcnt(0)
	v_mfma_f32_32x32x16_bf16 v[2:17], v[72:75], v[88:91], v[2:17]
	s_waitcnt vmcnt(5)
	s_barrier
	s_add_i32 m0, s28, 0x14000
	s_nop 0
	global_load_lds_dwordx4 v30, s[40:41]
	s_add_i32 m0, s29, 0x14000
	s_nop 0
	global_load_lds_dwordx4 v31, s[38:39]
	s_add_i32 m0, s29, 0x14400
	s_nop 0
	global_load_lds_dwordx4 v32, s[38:39]
	s_add_i32 m0, s29, 0x14800
	s_nop 0
	global_load_lds_dwordx4 v33, s[38:39]
	s_add_i32 m0, s29, 0x14c00
	s_nop 0
	global_load_lds_dwordx4 v34, s[38:39]
	s_add_u32 s40, s40, 0x80
	s_addc_u32 s41, s41, 0
	s_add_u32 s38, s38, 0x80
	s_addc_u32 s39, s39, 0
	ds_read_b128 v[60:63], v44
	ds_read_b128 v[76:79], v48
	ds_read_b128 v[64:67], v45
	ds_read_b128 v[80:83], v49
	ds_read_b128 v[68:71], v46
	ds_read_b128 v[84:87], v50
	ds_read_b128 v[72:75], v47
	ds_read_b128 v[88:91], v51
	s_waitcnt lgkmcnt(6)
	v_mfma_f32_32x32x16_bf16 v[2:17], v[60:63], v[76:79], v[2:17]
	s_waitcnt lgkmcnt(4)
	v_mfma_f32_32x32x16_bf16 v[2:17], v[64:67], v[80:83], v[2:17]
	s_waitcnt lgkmcnt(2)
	v_mfma_f32_32x32x16_bf16 v[2:17], v[68:71], v[84:87], v[2:17]
	s_waitcnt lgkmcnt(0)
	v_mfma_f32_32x32x16_bf16 v[2:17], v[72:75], v[88:91], v[2:17]
	s_waitcnt vmcnt(5)
	s_barrier
	s_add_i32 m0, s28, 0x0
	s_nop 0
	global_load_lds_dwordx4 v30, s[40:41]
	s_add_i32 m0, s29, 0x0
	s_nop 0
	global_load_lds_dwordx4 v31, s[38:39]
	s_add_i32 m0, s29, 0x400
	s_nop 0
	global_load_lds_dwordx4 v32, s[38:39]
	s_add_i32 m0, s29, 0x800
	s_nop 0
	global_load_lds_dwordx4 v33, s[38:39]
	s_add_i32 m0, s29, 0xc00
	s_nop 0
	global_load_lds_dwordx4 v34, s[38:39]
	s_add_u32 s40, s40, 0x80
	s_addc_u32 s41, s41, 0
	s_add_u32 s38, s38, 0x80
	s_addc_u32 s39, s39, 0
	ds_read_b128 v[60:63], v44 offset:40960
	ds_read_b128 v[76:79], v48 offset:40960
	ds_read_b128 v[64:67], v45 offset:40960
	ds_read_b128 v[80:83], v49 offset:40960
	ds_read_b128 v[68:71], v46 offset:40960
	ds_read_b128 v[84:87], v50 offset:40960
	ds_read_b128 v[72:75], v47 offset:40960
	ds_read_b128 v[88:91], v51 offset:40960
	s_waitcnt lgkmcnt(6)
	v_mfma_f32_32x32x16_bf16 v[2:17], v[60:63], v[76:79], v[2:17]
	s_waitcnt lgkmcnt(4)
	v_mfma_f32_32x32x16_bf16 v[2:17], v[64:67], v[80:83], v[2:17]
	s_waitcnt lgkmcnt(2)
	v_mfma_f32_32x32x16_bf16 v[2:17], v[68:71], v[84:87], v[2:17]
	s_waitcnt lgkmcnt(0)
	v_mfma_f32_32x32x16_bf16 v[2:17], v[72:75], v[88:91], v[2:17]
	s_waitcnt vmcnt(5)
	s_barrier
	s_add_i32 m0, s28, 0xa000
	s_nop 0
	global_load_lds_dwordx4 v30, s[40:41]
	s_add_i32 m0, s29, 0xa000
	s_nop 0
	global_load_lds_dwordx4 v31, s[38:39]
	s_add_i32 m0, s29, 0xa400
	s_nop 0
	global_load_lds_dwordx4 v32, s[38:39]
	s_add_i32 m0, s29, 0xa800
	s_nop 0
	global_load_lds_dwordx4 v33, s[38:39]
	s_add_i32 m0, s29, 0xac00
	s_nop 0
	global_load_lds_dwordx4 v34, s[38:39]
	s_add_u32 s40, s40, 0x80
	s_addc_u32 s41, s41, 0
	s_add_u32 s38, s38, 0x80
	s_addc_u32 s39, s39, 0
	ds_read_b128 v[60:63], v52
	ds_read_b128 v[76:79], v56
	ds_read_b128 v[64:67], v53
	ds_read_b128 v[80:83], v57
	ds_read_b128 v[68:71], v54
	ds_read_b128 v[84:87], v58
	ds_read_b128 v[72:75], v55
	ds_read_b128 v[88:91], v59
	s_waitcnt lgkmcnt(6)
	v_mfma_f32_32x32x16_bf16 v[2:17], v[60:63], v[76:79], v[2:17]
	s_waitcnt lgkmcnt(4)
	v_mfma_f32_32x32x16_bf16 v[2:17], v[64:67], v[80:83], v[2:17]
	s_waitcnt lgkmcnt(2)
	v_mfma_f32_32x32x16_bf16 v[2:17], v[68:71], v[84:87], v[2:17]
	s_waitcnt lgkmcnt(0)
	v_mfma_f32_32x32x16_bf16 v[2:17], v[72:75], v[88:91], v[2:17]
	s_waitcnt vmcnt(5)
	s_barrier
	s_add_i32 m0, s28, 0x14000
	s_nop 0
	global_load_lds_dwordx4 v30, s[40:41]
	s_add_i32 m0, s29, 0x14000
	s_nop 0
	global_load_lds_dwordx4 v31, s[38:39]
	s_add_i32 m0, s29, 0x14400
	s_nop 0
	global_load_lds_dwordx4 v32, s[38:39]
	s_add_i32 m0, s29, 0x14800
	s_nop 0
	global_load_lds_dwordx4 v33, s[38:39]
	s_add_i32 m0, s29, 0x14c00
	s_nop 0
	global_load_lds_dwordx4 v34, s[38:39]
	s_add_u32 s40, s40, 0x80
	s_addc_u32 s41, s41, 0
	s_add_u32 s38, s38, 0x80
	s_addc_u32 s39, s39, 0
	ds_read_b128 v[60:63], v44
	ds_read_b128 v[76:79], v48
	ds_read_b128 v[64:67], v45
	ds_read_b128 v[80:83], v49
	ds_read_b128 v[68:71], v46
	ds_read_b128 v[84:87], v50
	ds_read_b128 v[72:75], v47
	ds_read_b128 v[88:91], v51
	s_waitcnt lgkmcnt(6)
	v_mfma_f32_32x32x16_bf16 v[2:17], v[60:63], v[76:79], v[2:17]
	s_waitcnt lgkmcnt(4)
	v_mfma_f32_32x32x16_bf16 v[2:17], v[64:67], v[80:83], v[2:17]
	s_waitcnt lgkmcnt(2)
	v_mfma_f32_32x32x16_bf16 v[2:17], v[68:71], v[84:87], v[2:17]
	s_waitcnt lgkmcnt(0)
	v_mfma_f32_32x32x16_bf16 v[2:17], v[72:75], v[88:91], v[2:17]
	s_waitcnt vmcnt(5)
	s_barrier
	s_add_i32 m0, s28, 0x0
	s_nop 0
	global_load_lds_dwordx4 v30, s[40:41]
	s_add_i32 m0, s29, 0x0
	s_nop 0
	global_load_lds_dwordx4 v31, s[38:39]
	s_add_i32 m0, s29, 0x400
	s_nop 0
	global_load_lds_dwordx4 v32, s[38:39]
	s_add_i32 m0, s29, 0x800
	s_nop 0
	global_load_lds_dwordx4 v33, s[38:39]
	s_add_i32 m0, s29, 0xc00
	s_nop 0
	global_load_lds_dwordx4 v34, s[38:39]
	s_add_u32 s40, s40, 0x80
	s_addc_u32 s41, s41, 0
	s_add_u32 s38, s38, 0x80
	s_addc_u32 s39, s39, 0
	ds_read_b128 v[60:63], v44 offset:40960
	ds_read_b128 v[76:79], v48 offset:40960
	ds_read_b128 v[64:67], v45 offset:40960
	ds_read_b128 v[80:83], v49 offset:40960
	ds_read_b128 v[68:71], v46 offset:40960
	ds_read_b128 v[84:87], v50 offset:40960
	ds_read_b128 v[72:75], v47 offset:40960
	ds_read_b128 v[88:91], v51 offset:40960
	s_waitcnt lgkmcnt(6)
	v_mfma_f32_32x32x16_bf16 v[2:17], v[60:63], v[76:79], v[2:17]
	s_waitcnt lgkmcnt(4)
	v_mfma_f32_32x32x16_bf16 v[2:17], v[64:67], v[80:83], v[2:17]
	s_waitcnt lgkmcnt(2)
	v_mfma_f32_32x32x16_bf16 v[2:17], v[68:71], v[84:87], v[2:17]
	s_waitcnt lgkmcnt(0)
	v_mfma_f32_32x32x16_bf16 v[2:17], v[72:75], v[88:91], v[2:17]
	s_waitcnt vmcnt(5)
	s_barrier
	s_add_i32 m0, s28, 0xa000
	s_nop 0
	global_load_lds_dwordx4 v30, s[40:41]
	s_add_i32 m0, s29, 0xa000
	s_nop 0
	global_load_lds_dwordx4 v31, s[38:39]
	s_add_i32 m0, s29, 0xa400
	s_nop 0
	global_load_lds_dwordx4 v32, s[38:39]
	s_add_i32 m0, s29, 0xa800
	s_nop 0
	global_load_lds_dwordx4 v33, s[38:39]
	s_add_i32 m0, s29, 0xac00
	s_nop 0
	global_load_lds_dwordx4 v34, s[38:39]
	s_add_u32 s40, s40, 0x80
	s_addc_u32 s41, s41, 0
	s_add_u32 s38, s38, 0x80
	s_addc_u32 s39, s39, 0
	ds_read_b128 v[60:63], v52
	ds_read_b128 v[76:79], v56
	ds_read_b128 v[64:67], v53
	ds_read_b128 v[80:83], v57
	ds_read_b128 v[68:71], v54
	ds_read_b128 v[84:87], v58
	ds_read_b128 v[72:75], v55
	ds_read_b128 v[88:91], v59
	s_waitcnt lgkmcnt(6)
	v_mfma_f32_32x32x16_bf16 v[2:17], v[60:63], v[76:79], v[2:17]
	s_waitcnt lgkmcnt(4)
	v_mfma_f32_32x32x16_bf16 v[2:17], v[64:67], v[80:83], v[2:17]
	s_waitcnt lgkmcnt(2)
	v_mfma_f32_32x32x16_bf16 v[2:17], v[68:71], v[84:87], v[2:17]
	s_waitcnt lgkmcnt(0)
	v_mfma_f32_32x32x16_bf16 v[2:17], v[72:75], v[88:91], v[2:17]
	s_waitcnt vmcnt(5)
	s_barrier
	s_add_i32 m0, s28, 0x14000
	s_nop 0
	global_load_lds_dwordx4 v30, s[40:41]
	s_add_i32 m0, s29, 0x14000
	s_nop 0
	global_load_lds_dwordx4 v31, s[38:39]
	s_add_i32 m0, s29, 0x14400
	s_nop 0
	global_load_lds_dwordx4 v32, s[38:39]
	s_add_i32 m0, s29, 0x14800
	s_nop 0
	global_load_lds_dwordx4 v33, s[38:39]
	s_add_i32 m0, s29, 0x14c00
	s_nop 0
	global_load_lds_dwordx4 v34, s[38:39]
	s_add_u32 s40, s40, 0x80
	s_addc_u32 s41, s41, 0
	s_add_u32 s38, s38, 0x80
	s_addc_u32 s39, s39, 0
	ds_read_b128 v[60:63], v44
	ds_read_b128 v[76:79], v48
	ds_read_b128 v[64:67], v45
	ds_read_b128 v[80:83], v49
	ds_read_b128 v[68:71], v46
	ds_read_b128 v[84:87], v50
	ds_read_b128 v[72:75], v47
	ds_read_b128 v[88:91], v51
	s_waitcnt lgkmcnt(6)
	v_mfma_f32_32x32x16_bf16 v[2:17], v[60:63], v[76:79], v[2:17]
	s_waitcnt lgkmcnt(4)
	v_mfma_f32_32x32x16_bf16 v[2:17], v[64:67], v[80:83], v[2:17]
	s_waitcnt lgkmcnt(2)
	v_mfma_f32_32x32x16_bf16 v[2:17], v[68:71], v[84:87], v[2:17]
	s_waitcnt lgkmcnt(0)
	v_mfma_f32_32x32x16_bf16 v[2:17], v[72:75], v[88:91], v[2:17]
	s_waitcnt vmcnt(5)
	s_barrier
	s_add_i32 m0, s28, 0x0
	s_nop 0
	global_load_lds_dwordx4 v30, s[40:41]
	s_add_i32 m0, s29, 0x0
	s_nop 0
	global_load_lds_dwordx4 v31, s[38:39]
	s_add_i32 m0, s29, 0x400
	s_nop 0
	global_load_lds_dwordx4 v32, s[38:39]
	s_add_i32 m0, s29, 0x800
	s_nop 0
	global_load_lds_dwordx4 v33, s[38:39]
	s_add_i32 m0, s29, 0xc00
	s_nop 0
	global_load_lds_dwordx4 v34, s[38:39]
	s_add_u32 s40, s40, 0x80
	s_addc_u32 s41, s41, 0
	s_add_u32 s38, s38, 0x80
	s_addc_u32 s39, s39, 0
	ds_read_b128 v[60:63], v44 offset:40960
	ds_read_b128 v[76:79], v48 offset:40960
	ds_read_b128 v[64:67], v45 offset:40960
	ds_read_b128 v[80:83], v49 offset:40960
	ds_read_b128 v[68:71], v46 offset:40960
	ds_read_b128 v[84:87], v50 offset:40960
	ds_read_b128 v[72:75], v47 offset:40960
	ds_read_b128 v[88:91], v51 offset:40960
	s_waitcnt lgkmcnt(6)
	v_mfma_f32_32x32x16_bf16 v[2:17], v[60:63], v[76:79], v[2:17]
	s_waitcnt lgkmcnt(4)
	v_mfma_f32_32x32x16_bf16 v[2:17], v[64:67], v[80:83], v[2:17]
	s_waitcnt lgkmcnt(2)
	v_mfma_f32_32x32x16_bf16 v[2:17], v[68:71], v[84:87], v[2:17]
	s_waitcnt lgkmcnt(0)
	v_mfma_f32_32x32x16_bf16 v[2:17], v[72:75], v[88:91], v[2:17]
	s_waitcnt vmcnt(5)
	s_barrier
	s_add_i32 m0, s28, 0xa000
	s_nop 0
	global_load_lds_dwordx4 v30, s[40:41]
	s_add_i32 m0, s29, 0xa000
	s_nop 0
	global_load_lds_dwordx4 v31, s[38:39]
	s_add_i32 m0, s29, 0xa400
	s_nop 0
	global_load_lds_dwordx4 v32, s[38:39]
	s_add_i32 m0, s29, 0xa800
	s_nop 0
	global_load_lds_dwordx4 v33, s[38:39]
	s_add_i32 m0, s29, 0xac00
	s_nop 0
	global_load_lds_dwordx4 v34, s[38:39]
	s_add_u32 s40, s40, 0x80
	s_addc_u32 s41, s41, 0
	s_add_u32 s38, s38, 0x80
	s_addc_u32 s39, s39, 0
	ds_read_b128 v[60:63], v52
	ds_read_b128 v[76:79], v56
	ds_read_b128 v[64:67], v53
	ds_read_b128 v[80:83], v57
	ds_read_b128 v[68:71], v54
	ds_read_b128 v[84:87], v58
	ds_read_b128 v[72:75], v55
	ds_read_b128 v[88:91], v59
	s_waitcnt lgkmcnt(6)
	v_mfma_f32_32x32x16_bf16 v[2:17], v[60:63], v[76:79], v[2:17]
	s_waitcnt lgkmcnt(4)
	v_mfma_f32_32x32x16_bf16 v[2:17], v[64:67], v[80:83], v[2:17]
	s_waitcnt lgkmcnt(2)
	v_mfma_f32_32x32x16_bf16 v[2:17], v[68:71], v[84:87], v[2:17]
	s_waitcnt lgkmcnt(0)
	v_mfma_f32_32x32x16_bf16 v[2:17], v[72:75], v[88:91], v[2:17]
	s_waitcnt vmcnt(5)
	s_barrier
	s_add_i32 m0, s28, 0x14000
	s_nop 0
	global_load_lds_dwordx4 v30, s[40:41]
	s_add_i32 m0, s29, 0x14000
	s_nop 0
	global_load_lds_dwordx4 v31, s[38:39]
	s_add_i32 m0, s29, 0x14400
	s_nop 0
	global_load_lds_dwordx4 v32, s[38:39]
	s_add_i32 m0, s29, 0x14800
	s_nop 0
	global_load_lds_dwordx4 v33, s[38:39]
	s_add_i32 m0, s29, 0x14c00
	s_nop 0
	global_load_lds_dwordx4 v34, s[38:39]
	s_add_u32 s40, s40, 0x80
	s_addc_u32 s41, s41, 0
	s_add_u32 s38, s38, 0x80
	s_addc_u32 s39, s39, 0
	ds_read_b128 v[60:63], v44
	ds_read_b128 v[76:79], v48
	ds_read_b128 v[64:67], v45
	ds_read_b128 v[80:83], v49
	ds_read_b128 v[68:71], v46
	ds_read_b128 v[84:87], v50
	ds_read_b128 v[72:75], v47
	ds_read_b128 v[88:91], v51
	s_waitcnt lgkmcnt(6)
	v_mfma_f32_32x32x16_bf16 v[2:17], v[60:63], v[76:79], v[2:17]
	s_waitcnt lgkmcnt(4)
	v_mfma_f32_32x32x16_bf16 v[2:17], v[64:67], v[80:83], v[2:17]
	s_waitcnt lgkmcnt(2)
	v_mfma_f32_32x32x16_bf16 v[2:17], v[68:71], v[84:87], v[2:17]
	s_waitcnt lgkmcnt(0)
	v_mfma_f32_32x32x16_bf16 v[2:17], v[72:75], v[88:91], v[2:17]
	s_waitcnt vmcnt(5)
	s_barrier
	s_add_i32 m0, s28, 0x0
	s_nop 0
	global_load_lds_dwordx4 v30, s[40:41]
	s_add_i32 m0, s29, 0x0
	s_nop 0
	global_load_lds_dwordx4 v31, s[38:39]
	s_add_i32 m0, s29, 0x400
	s_nop 0
	global_load_lds_dwordx4 v32, s[38:39]
	s_add_i32 m0, s29, 0x800
	s_nop 0
	global_load_lds_dwordx4 v33, s[38:39]
	s_add_i32 m0, s29, 0xc00
	s_nop 0
	global_load_lds_dwordx4 v34, s[38:39]
	s_add_u32 s40, s40, 0x80
	s_addc_u32 s41, s41, 0
	s_add_u32 s38, s38, 0x80
	s_addc_u32 s39, s39, 0
	ds_read_b128 v[60:63], v44 offset:40960
	ds_read_b128 v[76:79], v48 offset:40960
	ds_read_b128 v[64:67], v45 offset:40960
	ds_read_b128 v[80:83], v49 offset:40960
	ds_read_b128 v[68:71], v46 offset:40960
	ds_read_b128 v[84:87], v50 offset:40960
	ds_read_b128 v[72:75], v47 offset:40960
	ds_read_b128 v[88:91], v51 offset:40960
	s_waitcnt lgkmcnt(6)
	v_mfma_f32_32x32x16_bf16 v[2:17], v[60:63], v[76:79], v[2:17]
	s_waitcnt lgkmcnt(4)
	v_mfma_f32_32x32x16_bf16 v[2:17], v[64:67], v[80:83], v[2:17]
	s_waitcnt lgkmcnt(2)
	v_mfma_f32_32x32x16_bf16 v[2:17], v[68:71], v[84:87], v[2:17]
	s_waitcnt lgkmcnt(0)
	v_mfma_f32_32x32x16_bf16 v[2:17], v[72:75], v[88:91], v[2:17]
	s_waitcnt vmcnt(5)
	s_barrier
	ds_read_b128 v[60:63], v52
	ds_read_b128 v[76:79], v56
	ds_read_b128 v[64:67], v53
	ds_read_b128 v[80:83], v57
	ds_read_b128 v[68:71], v54
	ds_read_b128 v[84:87], v58
	ds_read_b128 v[72:75], v55
	ds_read_b128 v[88:91], v59
	s_waitcnt lgkmcnt(6)
	v_mfma_f32_32x32x16_bf16 v[2:17], v[60:63], v[76:79], v[2:17]
	s_waitcnt lgkmcnt(4)
	v_mfma_f32_32x32x16_bf16 v[2:17], v[64:67], v[80:83], v[2:17]
	s_waitcnt lgkmcnt(2)
	v_mfma_f32_32x32x16_bf16 v[2:17], v[68:71], v[84:87], v[2:17]
	s_waitcnt lgkmcnt(0)
	v_mfma_f32_32x32x16_bf16 v[2:17], v[72:75], v[88:91], v[2:17]
	s_waitcnt vmcnt(0)
	s_barrier
	ds_read_b128 v[60:63], v44
	ds_read_b128 v[76:79], v48
	ds_read_b128 v[64:67], v45
	ds_read_b128 v[80:83], v49
	ds_read_b128 v[68:71], v46
	ds_read_b128 v[84:87], v50
	ds_read_b128 v[72:75], v47
	ds_read_b128 v[88:91], v51
	s_waitcnt lgkmcnt(6)
	v_mfma_f32_32x32x16_bf16 v[2:17], v[60:63], v[76:79], v[2:17]
	s_waitcnt lgkmcnt(4)
	v_mfma_f32_32x32x16_bf16 v[2:17], v[64:67], v[80:83], v[2:17]
	s_waitcnt lgkmcnt(2)
	v_mfma_f32_32x32x16_bf16 v[2:17], v[68:71], v[84:87], v[2:17]
	s_waitcnt lgkmcnt(0)
	v_mfma_f32_32x32x16_bf16 v[2:17], v[72:75], v[88:91], v[2:17]
	s_barrier
	s_nop 7
	s_nop 7
	s_lshl_b32 s13, s12, 5
	s_and_b32 s25, s13, 0x60
	s_cmp_lg_u32 s21, 1
	v_lshlrev_b32_e32 v21, 2, v19
	s_cbranch_scc1 .LBB0_160
	v_lshl_or_b32 v0, v28, 2, s25
	v_mul_u32_u24_e32 v0, 0x84, v0
	v_add3_u32 v0, 0, v21, v0
	v_add_u32_e32 v20, 0x400, v0
	ds_write2_b32 v0, v2, v3 offset1:33
	ds_write2_b32 v0, v4, v5 offset0:66 offset1:99
	ds_write2_b32 v20, v6, v7 offset0:8 offset1:41
	ds_write2_b32 v20, v8, v9 offset0:74 offset1:107
	v_add_u32_e32 v20, 0x800, v0
	v_add_u32_e32 v0, 0xc00, v0
	ds_write2_b32 v20, v10, v11 offset0:16 offset1:49
	ds_write2_b32 v20, v12, v13 offset0:82 offset1:115
	ds_write2_b32 v0, v14, v15 offset0:24 offset1:57
	ds_write2_b32 v0, v16, v17 offset0:90 offset1:123

.LBB0_514:
	s_add_i32 m0, s28, 0x18000
	v_lshl_add_u64 v[2:3], v[2:3], 0, s[34:35]
	s_waitcnt vmcnt(2)
	s_barrier
	global_load_lds_dwordx4 v[2:3], off
	v_lshl_add_u64 v[2:3], v[4:5], 0, s[34:35]
	s_add_i32 m0, s28, 0x1a000
	s_add_i32 s43, s28, 0x8000
	global_load_lds_dwordx4 v[2:3], off
	v_lshl_add_u64 v[2:3], v[10:11], 0, s[34:35]
	s_mov_b32 m0, s43
	s_add_i32 s44, s28, 0xa000
	global_load_lds_dwordx4 v[2:3], off
	v_lshl_add_u64 v[2:3], v[12:13], 0, s[34:35]
	s_mov_b32 m0, s44
	v_cndmask_b32_e64 v134, 0.5, 1.0, s[0:1]
	global_load_lds_dwordx4 v[2:3], off
	s_add_i32 m0, s28, 0x1c000
	v_lshl_add_u64 v[2:3], v[6:7], 0, s[34:35]
	global_load_lds_dwordx4 v[2:3], off
	v_lshl_add_u64 v[2:3], v[8:9], 0, s[34:35]
	s_add_i32 m0, s28, 0x1e000
	v_lshlrev_b32_e32 v6, 2, v231
	global_load_lds_dwordx4 v[2:3], off
	v_bfe_u32 v2, v231, 4, 2
	v_and_b32_e32 v3, 15, v231
	v_lshlrev_b32_e32 v4, 4, v2
	s_and_b32 s0, s19, 3
	s_lshr_b32 s45, s10, 6
	v_lshl_or_b32 v5, v3, 6, v4
	s_lshl_b32 s1, s11, 13
	v_and_b32_e32 v6, 32, v6
	v_bitop3_b32 v7, v5, s1, v6 bitop3:0xde
	s_lshl_b32 s1, s0, 12
	s_add_i32 s46, s45, -2
	s_cmpk_lt_u32 s18, 0x100
	v_lshl_or_b32 v97, s11, 6, v3
	v_bitop3_b32 v232, s1, v5, v6 bitop3:0xf6
	s_cselect_b64 s[10:11], -1, 0
	v_lshlrev_b32_e32 v5, 2, v2
	s_and_b32 s1, s18, 0xffffff00
	s_lshl_b32 s18, s0, 6
	v_lshl_or_b32 v233, s0, 5, v5
	v_cmp_eq_u32_e64 s[36:37], 0, v2
	s_or_b32 s1, s18, s1
	s_lshl_b32 s0, s0, 2
	v_add_u32_e32 v2, v14, v15
	v_or3_b32 v234, s1, v4, v3
	s_add_i32 s0, s0, 0
	v_add_lshl_u32 v2, v2, v16, 1
	v_mov_b32_e32 v3, v1
	s_add_i32 s0, s0, 0x20400
	v_lshl_add_u64 v[136:137], s[6:7], 0, v[2:3]
	v_add_u32_e32 v2, v17, v18
	s_waitcnt vmcnt(6)
	s_movk_i32 s1, 0x100
	v_lshlrev_b32_e32 v4, 4, v234
	v_readlane_b32 s18, v255, 15
	v_lshl_add_u32 v235, v97, 4, s0
	v_add_lshl_u32 v2, v2, v19, 1
	v_readlane_b32 s0, v254, 0
	v_cmp_gt_i32_e64 s[38:39], s1, v234
	v_readlane_b32 s19, v255, 16
	s_ashr_i32 s48, s18, 31
	v_lshl_add_u64 v[138:139], s[6:7], 0, v[2:3]
	v_add_u32_e32 v2, 0, v4
	s_mov_b32 s18, s0
	v_readlane_b32 s0, v254, 1
	s_mov_b32 s47, 0
	v_mov_b32_e32 v135, v134
	v_add_u32_e32 v236, 0, v7
	v_add_u32_e32 v237, 0x20400, v2
	s_mov_b32 s19, s0
	s_barrier
	v_readlane_b32 s1, v254, 2
	s_branch .LBB0_517
.Lhop_19:
	s_branch .LBB0_19
.LBB0_515:
	s_mov_b64 s[18:19], 0
